# attention: one lgkmcnt wait per two fragment reads (QK and PV), half the s_waitcnt issue slots
# speedup vs baseline: 1.0054x; 1.0054x over previous
.Latt_swa_nomasktest:
	ds_read_b128 v[210:213], v208 offset:0
	ds_read_b128 v[214:217], v208 offset:4608
	ds_read_b128 v[218:221], v208 offset:32
	ds_read_b128 v[222:225], v208 offset:4640
	s_waitcnt lgkmcnt(2)
	v_mfma_f32_32x32x16_bf16 v[64:79], v[210:213], v[96:99], v[154:169]
	ds_read_b128 v[210:213], v208 offset:64
	v_mfma_f32_32x32x16_bf16 v[32:47], v[214:217], v[96:99], v[154:169]
	ds_read_b128 v[214:217], v208 offset:4672
	s_waitcnt lgkmcnt(2)
	v_mfma_f32_32x32x16_bf16 v[64:79], v[218:221], v[100:103], v[64:79]
	ds_read_b128 v[218:221], v208 offset:96
	v_mfma_f32_32x32x16_bf16 v[32:47], v[222:225], v[100:103], v[32:47]
	ds_read_b128 v[222:225], v208 offset:4704
	s_waitcnt lgkmcnt(2)
	v_mfma_f32_32x32x16_bf16 v[64:79], v[210:213], v[104:107], v[64:79]
	v_mfma_f32_32x32x16_bf16 v[32:47], v[214:217], v[104:107], v[32:47]
	s_waitcnt lgkmcnt(0)
	v_mfma_f32_32x32x16_bf16 v[64:79], v[218:221], v[108:111], v[64:79]
	v_mfma_f32_32x32x16_bf16 v[32:47], v[222:225], v[108:111], v[32:47]
	ds_read_b128 v[210:213], v209 offset:27648
	ds_read_b128 v[214:217], v209 offset:32256
	ds_read_b128 v[218:221], v209 offset:27680
	ds_read_b128 v[222:225], v209 offset:32288
	s_nop 6
	s_nop 0
	s_cmp_lt_u32 s47, 4
	s_cbranch_scc1 .Latt_swa_nomask
	s_cmp_eq_u64 s[36:37], exec
	s_cbranch_scc1 .Latt_swa_nomask
	v_add_u32_e32 v48, s43, v127
	v_add_u32_e32 v49, 0xfffffe7f, v48
	v_cmp_lt_u32_e32 vcc, s50, v49
	v_add_u32_e32 v49, 0xfffffe9f, v48
	s_nop 0
	v_cndmask_b32_e32 v64, v233, v64, vcc
	v_cmp_lt_u32_e32 vcc, s50, v49
	v_add_u32_e32 v49, 0xfffffe80, v48
	s_nop 0
	v_cndmask_b32_e32 v32, v233, v32, vcc
	v_cmp_lt_u32_e32 vcc, s50, v49
	v_add_u32_e32 v49, 0xfffffea0, v48
	s_nop 0
	v_cndmask_b32_e32 v65, v233, v65, vcc
	v_cmp_lt_u32_e32 vcc, s50, v49
	v_add_u32_e32 v49, 0xfffffe81, v48
	s_nop 0
	v_cndmask_b32_e32 v33, v233, v33, vcc
	v_cmp_lt_u32_e32 vcc, s50, v49
	v_add_u32_e32 v49, 0xfffffea1, v48
	s_nop 0
	v_cndmask_b32_e32 v66, v233, v66, vcc
	v_cmp_lt_u32_e32 vcc, s50, v49
	v_add_u32_e32 v49, 0xfffffe82, v48
	s_nop 0
	v_cndmask_b32_e32 v34, v233, v34, vcc
	v_cmp_lt_u32_e32 vcc, s50, v49
	v_add_u32_e32 v49, 0xfffffea2, v48
	s_nop 0
	v_cndmask_b32_e32 v67, v233, v67, vcc
	v_cmp_lt_u32_e32 vcc, s50, v49
	v_add_u32_e32 v49, 0xfffffe83, v48
	s_nop 0
	v_cndmask_b32_e32 v35, v233, v35, vcc
	v_cmp_lt_u32_e32 vcc, s50, v49
	v_add_u32_e32 v49, 0xfffffea3, v48
	s_nop 0
	v_cndmask_b32_e32 v68, v233, v68, vcc
	v_cmp_lt_u32_e32 vcc, s50, v49
	v_add_u32_e32 v49, 0xfffffe84, v48
	s_nop 0
	v_cndmask_b32_e32 v36, v233, v36, vcc
	v_cmp_lt_u32_e32 vcc, s50, v49
	v_add_u32_e32 v49, 0xfffffea4, v48
	s_nop 0
	v_cndmask_b32_e32 v69, v233, v69, vcc
	v_cmp_lt_u32_e32 vcc, s50, v49
	v_add_u32_e32 v49, 0xfffffe85, v48
	s_nop 0
	v_cndmask_b32_e32 v37, v233, v37, vcc
	v_cmp_lt_u32_e32 vcc, s50, v49
	v_add_u32_e32 v49, 0xfffffea5, v48
	s_nop 0
	v_cndmask_b32_e32 v70, v233, v70, vcc
	v_cmp_lt_u32_e32 vcc, s50, v49
	v_add_u32_e32 v49, 0xfffffe86, v48
	s_nop 0
	v_cndmask_b32_e32 v38, v233, v38, vcc
	v_cmp_lt_u32_e32 vcc, s50, v49
	v_add_u32_e32 v49, 0xfffffea6, v48
	s_nop 0
	v_cndmask_b32_e32 v71, v233, v71, vcc
	v_cmp_lt_u32_e32 vcc, s50, v49
	v_add_u32_e32 v49, 0xfffffe8f, v48
	s_nop 0
	v_cndmask_b32_e32 v39, v233, v39, vcc
	v_cmp_lt_u32_e32 vcc, s50, v49
	v_add_u32_e32 v49, 0xfffffeaf, v48
	s_nop 0
	v_cndmask_b32_e32 v72, v233, v72, vcc
	v_cmp_lt_u32_e32 vcc, s50, v49
	v_add_u32_e32 v49, 0xfffffe90, v48
	s_nop 0
	v_cndmask_b32_e32 v40, v233, v40, vcc
	v_cmp_lt_u32_e32 vcc, s50, v49
	v_add_u32_e32 v49, 0xfffffeb0, v48
	s_nop 0
	v_cndmask_b32_e32 v73, v233, v73, vcc
	v_cmp_lt_u32_e32 vcc, s50, v49
	v_add_u32_e32 v49, 0xfffffe91, v48
	s_nop 0
	v_cndmask_b32_e32 v41, v233, v41, vcc
	v_cmp_lt_u32_e32 vcc, s50, v49
	v_add_u32_e32 v49, 0xfffffeb1, v48
	s_nop 0
	v_cndmask_b32_e32 v74, v233, v74, vcc
	v_cmp_lt_u32_e32 vcc, s50, v49
	v_add_u32_e32 v49, 0xfffffe92, v48
	s_nop 0
	v_cndmask_b32_e32 v42, v233, v42, vcc
	v_cmp_lt_u32_e32 vcc, s50, v49
	v_add_u32_e32 v49, 0xfffffeb2, v48
	s_nop 0
	v_cndmask_b32_e32 v75, v233, v75, vcc
	v_cmp_lt_u32_e32 vcc, s50, v49
	v_add_u32_e32 v49, 0xfffffe93, v48
	s_nop 0
	v_cndmask_b32_e32 v43, v233, v43, vcc
	v_cmp_lt_u32_e32 vcc, s50, v49
	v_add_u32_e32 v49, 0xfffffeb3, v48
	s_nop 0
	v_cndmask_b32_e32 v76, v233, v76, vcc
	v_cmp_lt_u32_e32 vcc, s50, v49
	v_add_u32_e32 v49, 0xfffffe94, v48
	s_nop 0
	v_cndmask_b32_e32 v44, v233, v44, vcc
	v_cmp_lt_u32_e32 vcc, s50, v49
	v_add_u32_e32 v49, 0xfffffeb4, v48
	s_nop 0
	v_cndmask_b32_e32 v77, v233, v77, vcc
	v_cmp_lt_u32_e32 vcc, s50, v49
	v_add_u32_e32 v49, 0xfffffe95, v48
	s_nop 0
	v_cndmask_b32_e32 v45, v233, v45, vcc
	v_cmp_lt_u32_e32 vcc, s50, v49
	v_add_u32_e32 v49, 0xfffffeb5, v48
	s_nop 0
	v_cndmask_b32_e32 v78, v233, v78, vcc
	v_cmp_lt_u32_e32 vcc, s50, v49
	v_add_u32_e32 v49, 0xfffffe96, v48
	v_add_u32_e32 v48, 0xfffffeb6, v48
	v_cndmask_b32_e32 v46, v233, v46, vcc
	v_cmp_lt_u32_e32 vcc, s50, v49
	s_nop 1
	v_cndmask_b32_e32 v79, v233, v79, vcc
	v_cmp_lt_u32_e32 vcc, s50, v48
	s_nop 1
	v_cndmask_b32_e32 v47, v233, v47, vcc

.Latt_swa_norescale:
	v_exp_f32_e32 v64, v64
	v_exp_f32_e32 v65, v65
	v_exp_f32_e32 v66, v66
	v_exp_f32_e32 v67, v67
	v_exp_f32_e32 v68, v68
	v_exp_f32_e32 v69, v69
	v_exp_f32_e32 v70, v70
	v_exp_f32_e32 v71, v71
	v_cvt_pk_bf16_f32 v170, v64, v65
	v_cvt_pk_bf16_f32 v171, v66, v67
	v_cvt_pk_bf16_f32 v172, v68, v69
	v_cvt_pk_bf16_f32 v173, v70, v71
	s_waitcnt lgkmcnt(2)
	s_nop 0
	v_mfma_f32_32x32x16_bf16 v[0:15], v[210:213], v[170:173], v[0:15]
	ds_read_b128 v[210:213], v209 offset:27712
	v_exp_f32_e32 v72, v72
	v_exp_f32_e32 v73, v73
	v_exp_f32_e32 v74, v74
	v_exp_f32_e32 v75, v75
	v_cvt_pk_bf16_f32 v174, v72, v73
	v_exp_f32_e32 v76, v76
	v_exp_f32_e32 v77, v77
	v_cvt_pk_bf16_f32 v175, v74, v75
	v_mfma_f32_32x32x16_bf16 v[16:31], v[214:217], v[170:173], v[16:31]
	ds_read_b128 v[214:217], v209 offset:32320
	v_exp_f32_e32 v78, v78
	v_exp_f32_e32 v79, v79
	v_cvt_pk_bf16_f32 v176, v76, v77
	v_cvt_pk_bf16_f32 v177, v78, v79
	v_add_f32_e32 v198, v64, v68
	v_add_f32_e32 v199, v65, v69
	v_add_f32_e32 v200, v66, v70
	v_add_f32_e32 v201, v67, v71
	s_waitcnt lgkmcnt(2)
	v_mfma_f32_32x32x16_bf16 v[0:15], v[218:221], v[174:177], v[0:15]
	ds_read_b128 v[218:221], v209 offset:27744
	v_exp_f32_e32 v32, v32
	v_exp_f32_e32 v33, v33
	v_exp_f32_e32 v34, v34
	v_exp_f32_e32 v35, v35
	v_cvt_pk_bf16_f32 v170, v32, v33
	v_exp_f32_e32 v36, v36
	v_exp_f32_e32 v37, v37
	v_cvt_pk_bf16_f32 v171, v34, v35
	v_exp_f32_e32 v38, v38
	v_exp_f32_e32 v39, v39
	v_mfma_f32_32x32x16_bf16 v[16:31], v[222:225], v[174:177], v[16:31]
	ds_read_b128 v[222:225], v209 offset:32352
	v_cvt_pk_bf16_f32 v172, v36, v37
	v_cvt_pk_bf16_f32 v173, v38, v39
	v_add_f32_e32 v198, v198, v72
	v_add_f32_e32 v199, v199, v73
	v_add_f32_e32 v200, v200, v74
	v_add_f32_e32 v201, v201, v75
	v_add_f32_e32 v198, v198, v76
	v_add_f32_e32 v199, v199, v77
	v_add_f32_e32 v200, v200, v78
	v_add_f32_e32 v201, v201, v79
	s_waitcnt lgkmcnt(2)
	v_mfma_f32_32x32x16_bf16 v[0:15], v[210:213], v[170:173], v[0:15]
	v_exp_f32_e32 v40, v40
	v_exp_f32_e32 v41, v41
	v_exp_f32_e32 v42, v42
	v_exp_f32_e32 v43, v43
	v_cvt_pk_bf16_f32 v174, v40, v41
	v_exp_f32_e32 v44, v44
	v_exp_f32_e32 v45, v45
	v_cvt_pk_bf16_f32 v175, v42, v43
	v_exp_f32_e32 v46, v46
	v_exp_f32_e32 v47, v47
	v_mfma_f32_32x32x16_bf16 v[16:31], v[214:217], v[170:173], v[16:31]
	v_cvt_pk_bf16_f32 v176, v44, v45
	v_cvt_pk_bf16_f32 v177, v46, v47
	v_add_f32_e32 v198, v198, v32
	v_add_f32_e32 v199, v199, v33
	v_add_f32_e32 v200, v200, v34
	v_add_f32_e32 v201, v201, v35
	v_add_f32_e32 v198, v198, v36
	v_add_f32_e32 v199, v199, v37
	v_add_f32_e32 v200, v200, v38
	v_add_f32_e32 v201, v201, v39
	s_waitcnt lgkmcnt(0)
	v_mfma_f32_32x32x16_bf16 v[0:15], v[218:221], v[174:177], v[0:15]
	v_add_f32_e32 v198, v198, v40
	v_add_f32_e32 v199, v199, v41
	v_add_f32_e32 v200, v200, v42
	v_add_f32_e32 v201, v201, v43
	v_mfma_f32_32x32x16_bf16 v[16:31], v[222:225], v[174:177], v[16:31]
	v_add_f32_e32 v198, v198, v44
	v_add_f32_e32 v199, v199, v45
	v_add_f32_e32 v200, v200, v46
	v_add_f32_e32 v201, v201, v47
	v_add_f32_e32 v198, v198, v199
	v_add_f32_e32 v200, v200, v201
	v_add_f32_e32 v198, v198, v200
	v_add_f32_e32 v121, v121, v198

.Latt_diff_dmaend:
	s_waitcnt lgkmcnt(2)
	v_mfma_f32_32x32x16_bf16 v[64:79], v[112:115], v[130:133], v[96:111]
	ds_read_b128 v[112:115], v242 offset:4608
	v_mfma_f32_32x32x16_bf16 v[64:79], v[116:119], v[134:137], v[64:79]
	ds_read_b128 v[116:119], v242 offset:4640
	s_waitcnt lgkmcnt(2)
	v_mfma_f32_32x32x16_bf16 v[64:79], v[120:123], v[138:141], v[64:79]
	ds_read_b128 v[120:123], v242 offset:4672
	v_mfma_f32_32x32x16_bf16 v[64:79], v[124:127], v[142:145], v[64:79]
	ds_read_b128 v[124:127], v242 offset:4704
	s_waitcnt lgkmcnt(2)
	v_mfma_f32_32x32x16_bf16 v[80:95], v[112:115], v[130:133], v[96:111]
	v_mfma_f32_32x32x16_bf16 v[80:95], v[116:119], v[134:137], v[80:95]
	s_waitcnt lgkmcnt(0)
	v_mfma_f32_32x32x16_bf16 v[80:95], v[120:123], v[138:141], v[80:95]
	v_mfma_f32_32x32x16_bf16 v[80:95], v[124:127], v[142:145], v[80:95]
	ds_read_b128 v[112:115], v243 offset:27648
	ds_read_b128 v[116:119], v243 offset:32256
	ds_read_b128 v[120:123], v243 offset:36864
	ds_read_b128 v[124:127], v243 offset:41472
	s_cmp_eq_u32 s52, 0
	s_cselect_b32 s31, 0xff7fffff, 0
	v_max3_f32 v227, v64, v65, v66
	v_max3_f32 v228, v67, v68, v69
	v_max3_f32 v227, v227, v70, v71
	v_max3_f32 v228, v228, v72, v73
	v_max3_f32 v227, v227, v74, v75
	v_max3_f32 v228, v228, v76, v77
	v_max3_f32 v227, v227, v78, v79
	v_max3_f32 v229, v80, v81, v82
	v_max3_f32 v226, v83, v84, v85
	v_max3_f32 v229, v229, v86, v87
	v_max3_f32 v226, v226, v88, v89
	v_max3_f32 v229, v229, v90, v91
	v_max3_f32 v226, v226, v92, v93
	v_max3_f32 v229, v229, v94, v95
	v_max3_f32 v226, v226, v227, v228
	v_max_f32_e32 v226, v226, v229
	v_cmp_lt_f32_e32 vcc, s58, v226
	s_cmp_eq_u32 s52, 0
	s_cbranch_scc1 .Latt_diff_rare
	s_cbranch_vccnz .Latt_diff_rare
.Latt_diff_norescale:
	v_exp_f32_e32 v64, v64
	v_exp_f32_e32 v65, v65
	v_exp_f32_e32 v66, v66
	v_exp_f32_e32 v67, v67
	v_exp_f32_e32 v68, v68
	v_exp_f32_e32 v69, v69
	v_exp_f32_e32 v70, v70
	v_exp_f32_e32 v71, v71
	v_cvt_pk_bf16_f32 v218, v64, v65
	v_cvt_pk_bf16_f32 v219, v66, v67
	v_cvt_pk_bf16_f32 v220, v68, v69
	v_cvt_pk_bf16_f32 v221, v70, v71
	s_waitcnt lgkmcnt(2)
	s_nop 0
	v_mfma_f32_32x32x16_bf16 v[0:15], v[112:115], v[218:221], v[0:15]
	ds_read_b128 v[112:115], v243 offset:27680
	v_exp_f32_e32 v72, v72
	v_exp_f32_e32 v73, v73
	v_exp_f32_e32 v74, v74
	v_exp_f32_e32 v75, v75
	v_mfma_f32_32x32x16_bf16 v[48:63], v[116:119], v[218:221], v[48:63]
	ds_read_b128 v[116:119], v243 offset:32288
	v_cvt_pk_bf16_f32 v222, v72, v73
	v_exp_f32_e32 v76, v76
	v_exp_f32_e32 v77, v77
	v_cvt_pk_bf16_f32 v223, v74, v75
	s_waitcnt lgkmcnt(2)
	v_mfma_f32_32x32x16_bf16 v[32:47], v[120:123], v[218:221], v[32:47]
	ds_read_b128 v[120:123], v243 offset:36896
	v_exp_f32_e32 v78, v78
	v_exp_f32_e32 v79, v79
	v_cvt_pk_bf16_f32 v224, v76, v77
	v_cvt_pk_bf16_f32 v225, v78, v79
	v_mfma_f32_32x32x16_bf16 v[16:31], v[124:127], v[218:221], v[16:31]
	ds_read_b128 v[124:127], v243 offset:41504
	v_add_f32_e32 v226, v64, v68
	v_add_f32_e32 v227, v65, v69
	v_add_f32_e32 v228, v66, v70
	v_add_f32_e32 v229, v67, v71
	s_waitcnt lgkmcnt(2)
	v_mfma_f32_32x32x16_bf16 v[0:15], v[112:115], v[222:225], v[0:15]
	ds_read_b128 v[112:115], v243 offset:27712
	v_exp_f32_e32 v80, v80
	v_exp_f32_e32 v81, v81
	v_exp_f32_e32 v82, v82
	v_exp_f32_e32 v83, v83
	v_cvt_pk_bf16_f32 v218, v80, v81
	v_mfma_f32_32x32x16_bf16 v[48:63], v[116:119], v[222:225], v[48:63]
	ds_read_b128 v[116:119], v243 offset:32320
	v_exp_f32_e32 v84, v84
	v_exp_f32_e32 v85, v85
	v_cvt_pk_bf16_f32 v219, v82, v83
	v_exp_f32_e32 v86, v86
	v_exp_f32_e32 v87, v87
	s_waitcnt lgkmcnt(2)
	v_mfma_f32_32x32x16_bf16 v[32:47], v[120:123], v[222:225], v[32:47]
	ds_read_b128 v[120:123], v243 offset:36928
	v_cvt_pk_bf16_f32 v220, v84, v85
	v_cvt_pk_bf16_f32 v221, v86, v87
	v_add_f32_e32 v226, v226, v72
	v_add_f32_e32 v227, v227, v73
	v_add_f32_e32 v228, v228, v74
	v_mfma_f32_32x32x16_bf16 v[16:31], v[124:127], v[222:225], v[16:31]
	ds_read_b128 v[124:127], v243 offset:41536
	v_add_f32_e32 v229, v229, v75
	v_add_f32_e32 v226, v226, v76
	v_add_f32_e32 v227, v227, v77
	v_add_f32_e32 v228, v228, v78
	v_add_f32_e32 v229, v229, v79
	s_waitcnt lgkmcnt(2)
	v_mfma_f32_32x32x16_bf16 v[0:15], v[112:115], v[218:221], v[0:15]
	ds_read_b128 v[112:115], v243 offset:27744
	v_exp_f32_e32 v88, v88
	v_exp_f32_e32 v89, v89
	v_exp_f32_e32 v90, v90
	v_exp_f32_e32 v91, v91
	v_cvt_pk_bf16_f32 v222, v88, v89
	v_mfma_f32_32x32x16_bf16 v[48:63], v[116:119], v[218:221], v[48:63]
	ds_read_b128 v[116:119], v243 offset:32352
	v_exp_f32_e32 v92, v92
	v_exp_f32_e32 v93, v93
	v_cvt_pk_bf16_f32 v223, v90, v91
	v_exp_f32_e32 v94, v94
	v_exp_f32_e32 v95, v95
	s_waitcnt lgkmcnt(2)
	v_mfma_f32_32x32x16_bf16 v[32:47], v[120:123], v[218:221], v[32:47]
	ds_read_b128 v[120:123], v243 offset:36960
	v_cvt_pk_bf16_f32 v224, v92, v93
	v_cvt_pk_bf16_f32 v225, v94, v95
	v_add_f32_e32 v226, v226, v80
	v_add_f32_e32 v227, v227, v81
	v_add_f32_e32 v228, v228, v82
	v_mfma_f32_32x32x16_bf16 v[16:31], v[124:127], v[218:221], v[16:31]
	ds_read_b128 v[124:127], v243 offset:41568
	v_add_f32_e32 v229, v229, v83
	v_add_f32_e32 v226, v226, v84
	v_add_f32_e32 v227, v227, v85
	v_add_f32_e32 v228, v228, v86
	v_add_f32_e32 v229, v229, v87
	s_waitcnt lgkmcnt(2)
	v_mfma_f32_32x32x16_bf16 v[0:15], v[112:115], v[222:225], v[0:15]
	v_add_f32_e32 v226, v226, v88
	v_add_f32_e32 v227, v227, v89
	v_mfma_f32_32x32x16_bf16 v[48:63], v[116:119], v[222:225], v[48:63]
	v_add_f32_e32 v228, v228, v90
	v_add_f32_e32 v229, v229, v91
	s_waitcnt lgkmcnt(0)
	v_mfma_f32_32x32x16_bf16 v[32:47], v[120:123], v[222:225], v[32:47]
	v_add_f32_e32 v226, v226, v92
	v_add_f32_e32 v227, v227, v93
	v_mfma_f32_32x32x16_bf16 v[16:31], v[124:127], v[222:225], v[16:31]
	v_add_f32_e32 v228, v228, v94
	v_add_f32_e32 v229, v229, v95
	v_add_f32_e32 v226, v226, v227
	v_add_f32_e32 v228, v228, v229
	v_add_f32_e32 v226, v226, v228
	v_add_f32_e32 v157, v157, v226

.Latt_mla_dmaend:
	s_waitcnt lgkmcnt(3)
	v_mfma_f32_32x32x16_bf16 v[64:79], v[112:115], v[130:133], v[96:111]
	ds_read_b128 v[112:115], v209 offset:160
	v_mfma_f32_32x32x16_bf16 v[64:79], v[116:119], v[134:137], v[64:79]
	ds_read_b128 v[116:119], v209 offset:192
	s_waitcnt lgkmcnt(3)
	v_mfma_f32_32x32x16_bf16 v[64:79], v[120:123], v[138:141], v[64:79]
	ds_read_b128 v[120:123], v209 offset:224
	v_mfma_f32_32x32x16_bf16 v[64:79], v[124:127], v[142:145], v[64:79]
	ds_read_b128 v[124:127], v209 offset:256
	s_waitcnt lgkmcnt(3)
	v_mfma_f32_32x32x16_bf16 v[64:79], v[250:253], v[146:149], v[64:79]
	ds_read_b128 v[250:253], v209 offset:288
	v_mfma_f32_32x32x16_bf16 v[64:79], v[112:115], v[150:153], v[64:79]
	ds_read_b128 v[112:115], v209 offset:320
	s_waitcnt lgkmcnt(3)
	v_mfma_f32_32x32x16_bf16 v[64:79], v[116:119], v[154:157], v[64:79]
	ds_read_b128 v[116:119], v209 offset:352
	v_mfma_f32_32x32x16_bf16 v[64:79], v[120:123], v[158:161], v[64:79]
	ds_read_b128 v[120:123], v209 offset:12800
	s_waitcnt lgkmcnt(3)
	v_mfma_f32_32x32x16_bf16 v[64:79], v[124:127], v[162:165], v[64:79]
	ds_read_b128 v[124:127], v209 offset:12832
	v_mfma_f32_32x32x16_bf16 v[64:79], v[250:253], v[166:169], v[64:79]
	ds_read_b128 v[250:253], v209 offset:12864
	s_waitcnt lgkmcnt(3)
	v_mfma_f32_32x32x16_bf16 v[64:79], v[112:115], v[170:173], v[64:79]
	ds_read_b128 v[112:115], v209 offset:12896
	v_mfma_f32_32x32x16_bf16 v[64:79], v[116:119], v[174:177], v[64:79]
	ds_read_b128 v[116:119], v209 offset:12928
	s_waitcnt lgkmcnt(3)
	v_mfma_f32_32x32x16_bf16 v[80:95], v[120:123], v[130:133], v[96:111]
	ds_read_b128 v[120:123], v209 offset:12960
	v_mfma_f32_32x32x16_bf16 v[80:95], v[124:127], v[134:137], v[80:95]
	ds_read_b128 v[124:127], v209 offset:12992
	s_waitcnt lgkmcnt(3)
	v_mfma_f32_32x32x16_bf16 v[80:95], v[250:253], v[138:141], v[80:95]
	ds_read_b128 v[250:253], v209 offset:13024
	v_mfma_f32_32x32x16_bf16 v[80:95], v[112:115], v[142:145], v[80:95]
	ds_read_b128 v[112:115], v209 offset:13056
	s_waitcnt lgkmcnt(3)
	v_mfma_f32_32x32x16_bf16 v[80:95], v[116:119], v[146:149], v[80:95]
	ds_read_b128 v[116:119], v209 offset:13088
	v_max3_f32 v211, v64, v65, v66
	v_mfma_f32_32x32x16_bf16 v[80:95], v[120:123], v[150:153], v[80:95]
	ds_read_b128 v[120:123], v209 offset:13120
	v_max3_f32 v213, v67, v68, v69
	s_waitcnt lgkmcnt(3)
	v_mfma_f32_32x32x16_bf16 v[80:95], v[124:127], v[154:157], v[80:95]
	ds_read_b128 v[124:127], v209 offset:13152
	v_max3_f32 v211, v211, v70, v71
	v_mfma_f32_32x32x16_bf16 v[80:95], v[250:253], v[158:161], v[80:95]
	v_max3_f32 v213, v213, v72, v73
	s_waitcnt lgkmcnt(2)
	v_mfma_f32_32x32x16_bf16 v[80:95], v[112:115], v[162:165], v[80:95]
	v_max3_f32 v211, v211, v74, v75
	v_mfma_f32_32x32x16_bf16 v[80:95], v[116:119], v[166:169], v[80:95]
	v_max3_f32 v213, v213, v76, v77
	s_waitcnt lgkmcnt(0)
	v_mfma_f32_32x32x16_bf16 v[80:95], v[120:123], v[170:173], v[80:95]
	v_max3_f32 v211, v211, v78, v79
	v_mfma_f32_32x32x16_bf16 v[80:95], v[124:127], v[174:177], v[80:95]
	ds_read_b128 v[112:115], v219 offset:0
	ds_read_b128 v[116:119], v219 offset:4608
	ds_read_b128 v[120:123], v219 offset:9216
	s_cmp_eq_u32 s55, 0
	s_cselect_b32 s31, 0xff7fffff, 0
	s_nop 6
	v_max3_f32 v215, v80, v81, v82
	v_max3_f32 v209, v83, v84, v85
	v_max3_f32 v215, v215, v86, v87
	v_max3_f32 v209, v209, v88, v89
	v_max3_f32 v215, v215, v90, v91
	v_max3_f32 v209, v209, v92, v93
	v_max3_f32 v215, v215, v94, v95
	v_max3_f32 v209, v209, v211, v213
	v_max_f32_e32 v209, v209, v215
	v_cmp_lt_f32_e32 vcc, s58, v209
	s_cmp_eq_u32 s55, 0
	s_cbranch_scc1 .Latt_mla_rare
	s_cbranch_vccnz .Latt_mla_rare
.Latt_mla_norescale:
	v_exp_f32_e32 v64, v64
	v_exp_f32_e32 v65, v65
	v_exp_f32_e32 v66, v66
	v_exp_f32_e32 v67, v67
	v_exp_f32_e32 v68, v68
	v_exp_f32_e32 v69, v69
	v_exp_f32_e32 v70, v70
	v_exp_f32_e32 v71, v71
	v_cvt_pk_bf16_f32 v124, v64, v65
	v_cvt_pk_bf16_f32 v125, v66, v67
	v_cvt_pk_bf16_f32 v126, v68, v69
	v_cvt_pk_bf16_f32 v127, v70, v71
	s_waitcnt lgkmcnt(1)
	s_nop 0
	v_mfma_f32_32x32x16_bf16 v[48:63], v[112:115], v[124:127], v[48:63]
	ds_read_b128 v[112:115], v219 offset:13824
	v_exp_f32_e32 v72, v72
	v_exp_f32_e32 v73, v73
	v_exp_f32_e32 v74, v74
	v_exp_f32_e32 v75, v75
	v_mfma_f32_32x32x16_bf16 v[32:47], v[116:119], v[124:127], v[32:47]
	ds_read_b128 v[116:119], v219 offset:32
	v_cvt_pk_bf16_f32 v250, v72, v73
	v_exp_f32_e32 v76, v76
	v_exp_f32_e32 v77, v77
	v_cvt_pk_bf16_f32 v251, v74, v75
	s_waitcnt lgkmcnt(1)
	v_mfma_f32_32x32x16_bf16 v[16:31], v[120:123], v[124:127], v[16:31]
	ds_read_b128 v[120:123], v219 offset:4640
	v_exp_f32_e32 v78, v78
	v_exp_f32_e32 v79, v79
	v_cvt_pk_bf16_f32 v252, v76, v77
	v_cvt_pk_bf16_f32 v253, v78, v79
	v_mfma_f32_32x32x16_bf16 v[0:15], v[112:115], v[124:127], v[0:15]
	ds_read_b128 v[112:115], v219 offset:9248
	v_add_f32_e32 v209, v64, v68
	v_add_f32_e32 v211, v65, v69
	v_add_f32_e32 v213, v66, v70
	v_add_f32_e32 v215, v67, v71
	s_waitcnt lgkmcnt(1)
	v_mfma_f32_32x32x16_bf16 v[48:63], v[116:119], v[250:253], v[48:63]
	ds_read_b128 v[64:67], v219 offset:13856
	ds_read_b128 v[68:71], v219 offset:64
	v_exp_f32_e32 v80, v80
	v_exp_f32_e32 v81, v81
	v_exp_f32_e32 v82, v82
	v_exp_f32_e32 v83, v83
	v_cvt_pk_bf16_f32 v124, v80, v81
	v_mfma_f32_32x32x16_bf16 v[32:47], v[120:123], v[250:253], v[32:47]
	ds_read_b128 v[116:119], v219 offset:4672
	ds_read_b128 v[120:123], v219 offset:9280
	v_exp_f32_e32 v84, v84
	v_exp_f32_e32 v85, v85
	v_cvt_pk_bf16_f32 v125, v82, v83
	v_exp_f32_e32 v86, v86
	v_exp_f32_e32 v87, v87
	s_waitcnt lgkmcnt(3)
	v_mfma_f32_32x32x16_bf16 v[16:31], v[112:115], v[250:253], v[16:31]
	ds_read_b128 v[112:115], v219 offset:13888
	v_cvt_pk_bf16_f32 v126, v84, v85
	v_cvt_pk_bf16_f32 v127, v86, v87
	v_add_f32_e32 v209, v209, v72
	v_add_f32_e32 v211, v211, v73
	v_add_f32_e32 v213, v213, v74
	v_mfma_f32_32x32x16_bf16 v[0:15], v[64:67], v[250:253], v[0:15]
	ds_read_b128 v[64:67], v219 offset:96
	v_add_f32_e32 v215, v215, v75
	v_add_f32_e32 v209, v209, v76
	v_add_f32_e32 v211, v211, v77
	v_add_f32_e32 v213, v213, v78
	v_add_f32_e32 v215, v215, v79
	s_waitcnt lgkmcnt(3)
	v_mfma_f32_32x32x16_bf16 v[48:63], v[68:71], v[124:127], v[48:63]
	ds_read_b128 v[72:75], v219 offset:4704
	ds_read_b128 v[76:79], v219 offset:9312
	v_exp_f32_e32 v88, v88
	v_exp_f32_e32 v89, v89
	v_exp_f32_e32 v90, v90
	v_exp_f32_e32 v91, v91
	v_cvt_pk_bf16_f32 v250, v88, v89
	v_mfma_f32_32x32x16_bf16 v[32:47], v[116:119], v[124:127], v[32:47]
	ds_read_b128 v[68:71], v219 offset:13920
	v_exp_f32_e32 v92, v92
	v_exp_f32_e32 v93, v93
	v_cvt_pk_bf16_f32 v251, v90, v91
	v_exp_f32_e32 v94, v94
	v_exp_f32_e32 v95, v95
	s_waitcnt lgkmcnt(4)
	v_mfma_f32_32x32x16_bf16 v[16:31], v[120:123], v[124:127], v[16:31]
	v_cvt_pk_bf16_f32 v252, v92, v93
	v_cvt_pk_bf16_f32 v253, v94, v95
	v_add_f32_e32 v209, v209, v80
	v_add_f32_e32 v211, v211, v81
	v_add_f32_e32 v213, v213, v82
	v_mfma_f32_32x32x16_bf16 v[0:15], v[112:115], v[124:127], v[0:15]
	v_add_f32_e32 v215, v215, v83
	v_add_f32_e32 v209, v209, v84
	v_add_f32_e32 v211, v211, v85
	v_add_f32_e32 v213, v213, v86
	v_add_f32_e32 v215, v215, v87
	s_waitcnt lgkmcnt(2)
	v_mfma_f32_32x32x16_bf16 v[48:63], v[64:67], v[250:253], v[48:63]
	v_add_f32_e32 v209, v209, v88
	v_add_f32_e32 v211, v211, v89
	v_mfma_f32_32x32x16_bf16 v[32:47], v[72:75], v[250:253], v[32:47]
	v_add_f32_e32 v213, v213, v90
	v_add_f32_e32 v215, v215, v91
	s_waitcnt lgkmcnt(0)
	v_mfma_f32_32x32x16_bf16 v[16:31], v[76:79], v[250:253], v[16:31]
	v_add_f32_e32 v209, v209, v92
	v_add_f32_e32 v211, v211, v93
	v_mfma_f32_32x32x16_bf16 v[0:15], v[68:71], v[250:253], v[0:15]
	v_add_f32_e32 v213, v213, v94
	v_add_f32_e32 v215, v215, v95
	v_add_f32_e32 v209, v209, v211
	v_add_f32_e32 v213, v213, v215
	v_add_f32_e32 v209, v209, v213
	v_add_f32_e32 v205, v205, v209
